# no grid barrier after the FFN-down phase (next phase touches disjoint data; following barrier still orders it)
# speedup vs baseline: 1.0058x; 1.0048x over previous
; __device__ __forceinline__ void xcd_barrier(const XcdBarrier& b) {
;   asm volatile("s_waitcnt vmcnt(0)" ::: "memory");
;   __syncthreads();
;   if (threadIdx.x == 0) {
;     unsigned* bar = b.bar;
;     __builtin_amdgcn_s_waitcnt(0);
;     unsigned nloc = b.st[0], nx = b.st[1];
;     if (nloc == 0u) { xcd_barrier_complete(bar, b.x, nloc, nx); b.st[0] = nloc; b.st[1] = nx; }
; __global__ void __launch_bounds__(NTHR, 2) mega(Params p) {
;     ...
;     if (is_gemm) gemm_phase(lds, gm, E);
;     if (sync_after) xcd_barrier(xb);
.LBB0_1255:
	v_readlane_b32 s64, v254, 38
	v_readlane_b32 s0, v255, 25
	v_readlane_b32 s65, v254, 39
	v_readlane_b32 s66, v254, 40
	v_readlane_b32 s67, v254, 41
	v_readlane_b32 s68, v254, 42
	v_readlane_b32 s69, v254, 43
	v_readlane_b32 s70, v254, 44
	v_readlane_b32 s71, v254, 45
	v_readlane_b32 s72, v254, 46
	v_readlane_b32 s73, v254, 47
	v_readlane_b32 s74, v254, 48
	v_readlane_b32 s75, v254, 49
	v_readlane_b32 s1, v255, 26
	v_readlane_b32 s38, v254, 55
	v_readlane_b32 s40, v254, 57
	v_readlane_b32 s42, v254, 59
	v_readlane_b32 s48, v254, 61
	v_readlane_b32 s50, v254, 63
	v_readlane_b32 s52, v255, 1
	v_readlane_b32 s58, v255, 3
	v_readlane_b32 s60, v255, 5
	v_readlane_b32 s62, v255, 7
	v_readlane_b32 s64, v255, 9
	v_readlane_b32 s66, v255, 11
	v_readlane_b32 s68, v255, 13
	v_readlane_b32 s70, v255, 15
	v_readlane_b32 s72, v255, 17
	v_readlane_b32 s74, v255, 19
	v_readlane_b32 s28, v255, 21
	s_andn2_b64 vcc, exec, s[0:1]
	v_readlane_b32 s90, v254, 36
	v_readlane_b32 s36, v254, 54
	v_readlane_b32 s39, v254, 56
	v_readlane_b32 s41, v254, 58
	v_readlane_b32 s43, v254, 60
	v_readlane_b32 s49, v254, 62
	v_readlane_b32 s51, v255, 0
	v_readlane_b32 s53, v255, 2
	v_readlane_b32 s59, v255, 4
	v_readlane_b32 s61, v255, 6
	v_readlane_b32 s63, v255, 8
	v_readlane_b32 s65, v255, 10
	v_readlane_b32 s67, v255, 12
	v_readlane_b32 s69, v255, 14
	v_readlane_b32 s71, v255, 16
	v_readlane_b32 s73, v255, 18
	v_readlane_b32 s75, v255, 20
	v_readlane_b32 s29, v255, 22
	v_readlane_b32 s76, v254, 50
	v_readlane_b32 s77, v254, 51
	v_readlane_b32 s78, v254, 52
	v_readlane_b32 s79, v254, 53
	v_readlane_b32 s91, v254, 37
	s_cmp_eq_u32 s55, 16
	s_cbranch_scc1 .LBB0_223
	s_cmp_eq_u32 s55, 33
	s_cbranch_scc1 .LBB0_223
	s_cmp_eq_u32 s55, 50
	s_cbranch_scc1 .LBB0_223
	s_cbranch_vccnz .LBB0_223
	s_waitcnt vmcnt(0)
	s_waitcnt vmcnt(0) lgkmcnt(0)
	s_barrier
	s_mov_b64 s[0:1], exec
	v_readlane_b32 s2, v253, 1
	v_readlane_b32 s3, v253, 2
	s_and_b64 s[2:3], s[0:1], s[2:3]
	s_mov_b64 exec, s[2:3]
	s_cbranch_execz .LBB0_222
	v_readlane_b32 s2, v254, 34
	s_waitcnt vmcnt(0) expcnt(0) lgkmcnt(0)
	s_nop 0
	v_mov_b32_e32 v0, s2
	ds_read_b32 v2, v0
	v_readlane_b32 s2, v254, 35
	s_waitcnt lgkmcnt(0)
	v_cmp_ne_u32_e32 vcc, 0, v2
	v_mov_b32_e32 v0, s2
	ds_read_b32 v0, v0
	s_cbranch_vccnz .LBB0_1272
	s_mov_b32 s12, 1
	s_branch .LBB0_1260
